# wave reductions in NORM prompt loop (4 chains) and GATE (4 chains): ds_bpermute round trips replaced by DPP row ops + readlane (same butterfly tree)
# speedup vs baseline: 1.0054x; 1.0054x over previous
; __device__ __forceinline__ unsigned cvt_pk_bf16(float lo, float hi) { f32x2 v = {lo, hi}; bf16x2_t b = __builtin_convertvector(v, bf16x2_t); return __builtin_bit_cast(unsigned, b); }
; __device__ __forceinline__ float bflo(unsigned w) { return __uint_as_float(w << 16); }
; __device__ __forceinline__ float bfhi(unsigned w) { return __uint_as_float(w & 0xffff0000u); }
; __device__ __forceinline__ float silu_f(float g) { return g * __builtin_amdgcn_rcpf(1.0f + __expf(-g)); }
; __device__ __forceinline__ float wave_sum(float v) {
; #pragma unroll
;     for (int o = 1; o < 64; o <<= 1) v += __shfl_xor(v, o);
;     return v;
; __device__ __forceinline__ void gate_phase(const Ctx& c) {
;     ...
;         for (int u = 0; u < U; ++u) {
;             const int it = it0 + u * c.ngw;
;             if (it < NIT) {
;                 const int row = it >> 2, col = (it & 3) * 512 + c.lane * 8;
;                 float y[8] = {bflo(yv[u].x), bfhi(yv[u].x), bflo(yv[u].y), bfhi(yv[u].y), bflo(yv[u].z), bfhi(yv[u].z), bflo(yv[u].w), bfhi(yv[u].w)};
;                 const float z[8] = {bflo(zv[u].x), bfhi(zv[u].x), bflo(zv[u].y), bfhi(zv[u].y), bflo(zv[u].z), bfhi(zv[u].z), bflo(zv[u].w), bfhi(zv[u].w)};
;                 float ss = 0.f;
; #pragma unroll
;                 for (int j = 0; j < 8; ++j) { y[j] *= silu_f(z[j]); ss += y[j] * y[j]; }
;                 const float rs = rsqrtf(wave_sum(ss) * (1.0f / 512.0f) + EPS);
;                 const f32x4 n0 = *(const f32x4*)(nw + col), n1 = *(const f32x4*)(nw + col + 4);
;                 u32x4 o; o.x = cvt_pk_bf16(y[0] * rs * n0[0], y[1] * rs * n0[1]); o.y = cvt_pk_bf16(y[2] * rs * n0[2], y[3] * rs * n0[3]);
;                 o.z = cvt_pk_bf16(y[4] * rs * n1[0], y[5] * rs * n1[1]); o.w = cvt_pk_bf16(y[6] * rs * n1[2], y[7] * rs * n1[3]);
;                 *(u32x4*)(Z + (size_t)row * DIN + col) = o;
.LBB0_128:
	s_waitcnt vmcnt(0)
	v_lshlrev_b32_e32 v50, 16, v35
	v_and_b32_e32 v51, 0xffff0000, v35
	v_mul_f32_e32 v35, 0xbfb8aa3b, v50
	v_exp_f32_e32 v35, v35
	v_mul_f32_e32 v42, 0xbfb8aa3b, v51
	v_exp_f32_e32 v42, v42
	v_lshlrev_b32_e32 v52, 2, v1
	v_add_f32_e32 v1, 1.0, v35
	v_rcp_f32_e32 v54, v1
	v_add_f32_e32 v1, 1.0, v42
	v_rcp_f32_e32 v55, v1
	v_lshlrev_b32_e32 v56, 16, v31
	v_and_b32_e32 v57, 0xffff0000, v31
	v_readlane_b32 s48, v251, 16
	v_pk_mul_f32 v[50:51], v[54:55], v[50:51]
	v_lshlrev_b32_e32 v54, 16, v34
	v_and_b32_e32 v55, 0xffff0000, v34
	v_mul_f32_e32 v1, 0xbfb8aa3b, v54
	v_exp_f32_e32 v1, v1
	v_mul_f32_e32 v31, 0xbfb8aa3b, v55
	v_exp_f32_e32 v31, v31
	v_pk_mul_f32 v[34:35], v[50:51], v[56:57]
	v_add_f32_e32 v1, 1.0, v1
	v_rcp_f32_e32 v50, v1
	v_add_f32_e32 v1, 1.0, v31
	v_rcp_f32_e32 v51, v1
	v_readlane_b32 s56, v251, 24
	v_readlane_b32 s57, v251, 25
	s_nop 4
	global_load_dwordx4 v[42:45], v52, s[56:57] offset:16
	global_load_dwordx4 v[46:49], v52, s[56:57]
	v_lshlrev_b32_e32 v58, 16, v30
	v_and_b32_e32 v59, 0xffff0000, v30
	v_pk_mul_f32 v[30:31], v[50:51], v[54:55]
	v_lshlrev_b32_e32 v50, 16, v33
	v_and_b32_e32 v51, 0xffff0000, v33
	v_mul_f32_e32 v1, 0xbfb8aa3b, v50
	v_exp_f32_e32 v1, v1
	v_mul_f32_e32 v33, 0xbfb8aa3b, v51
	v_exp_f32_e32 v33, v33
	v_pk_mul_f32 v[54:55], v[30:31], v[58:59]
	v_add_f32_e32 v1, 1.0, v1
	v_rcp_f32_e32 v30, v1
	v_add_f32_e32 v1, 1.0, v33
	v_rcp_f32_e32 v31, v1
	v_lshlrev_b32_e32 v60, 16, v29
	v_and_b32_e32 v61, 0xffff0000, v29
	v_lshlrev_b32_e32 v62, 16, v28
	v_pk_mul_f32 v[30:31], v[30:31], v[50:51]
	v_lshlrev_b32_e32 v50, 16, v32
	v_and_b32_e32 v51, 0xffff0000, v32
	v_mul_f32_e32 v1, 0xbfb8aa3b, v50
	v_exp_f32_e32 v1, v1
	v_mul_f32_e32 v29, 0xbfb8aa3b, v51
	v_exp_f32_e32 v29, v29
	v_pk_mul_f32 v[32:33], v[30:31], v[60:61]
	v_add_f32_e32 v1, 1.0, v1
	v_rcp_f32_e32 v30, v1
	v_add_f32_e32 v1, 1.0, v29
	v_rcp_f32_e32 v31, v1
	v_and_b32_e32 v63, 0xffff0000, v28
	v_pk_mul_f32 v[60:61], v[32:33], v[32:33]
	v_pk_mul_f32 v[58:59], v[54:55], v[54:55]
	v_pk_mul_f32 v[28:29], v[30:31], v[50:51]
	v_pk_mul_f32 v[56:57], v[34:35], v[34:35]
	v_pk_mul_f32 v[30:31], v[28:29], v[62:63]
	v_mov_b32_e32 v53, v2
	v_pk_mul_f32 v[28:29], v[30:31], v[30:31]
	v_readlane_b32 s49, v251, 17
	v_add_f32_e32 v1, v28, v29
	v_add_f32_e32 v1, v60, v1
	v_add_f32_e32 v1, v61, v1
	v_add_f32_e32 v1, v58, v1
	v_add_f32_e32 v1, v59, v1
	v_add_f32_e32 v1, v56, v1
	v_add_f32_e32 v1, v57, v1
	s_nop 1
	v_add_f32_dpp v28, v1, v1 quad_perm:[1,0,3,2] row_mask:0xf bank_mask:0xf
	s_nop 1
	v_add_f32_dpp v28, v28, v28 quad_perm:[2,3,0,1] row_mask:0xf bank_mask:0xf
	s_nop 1
	v_add_f32_dpp v28, v28, v28 row_half_mirror row_mask:0xf bank_mask:0xf
	s_nop 1
	v_add_f32_dpp v28, v28, v28 row_mirror row_mask:0xf bank_mask:0xf
	s_nop 1
	v_add_f32_dpp v28, v28, v28 row_bcast:15 row_mask:0xa bank_mask:0xf
	s_nop 1
	v_add_f32_dpp v28, v28, v28 row_bcast:31 row_mask:0xc bank_mask:0xf
	s_nop 0
	v_readlane_b32 s32, v28, 63
	s_nop 1
	v_mov_b32_e32 v28, s32
	v_readlane_b32 s50, v251, 18
	v_readlane_b32 s51, v251, 19
	v_readlane_b32 s52, v251, 20
	v_readlane_b32 s53, v251, 21
	v_readlane_b32 s54, v251, 22
	v_readlane_b32 s55, v251, 23
	v_readlane_b32 s58, v251, 26
	v_readlane_b32 s59, v251, 27
	v_readlane_b32 s60, v251, 28
	v_readlane_b32 s61, v251, 29
	v_readlane_b32 s62, v251, 30
	v_readlane_b32 s63, v251, 31
	v_mov_b32_e32 v1, v2
	v_lshl_add_u64 v[50:51], s[8:9], 0, v[0:1]
	v_fmamk_f32 v28, v28, 0x3b000000, v228
	v_mul_f32_e32 v29, 0x4b800000, v28
	v_cmp_gt_f32_e32 vcc, s37, v28
	s_nop 1
	v_cndmask_b32_e32 v28, v28, v29, vcc
	v_rsq_f32_e32 v56, v28
	v_lshl_add_u64 v[28:29], s[56:57], 0, v[52:53]
	v_mul_f32_e32 v1, 0x45800000, v56
	v_cndmask_b32_e32 v52, v56, v1, vcc
	v_pk_mul_f32 v[30:31], v[30:31], v[52:53] op_sel_hi:[1,0]
	v_pk_mul_f32 v[32:33], v[32:33], v[52:53] op_sel_hi:[1,0]
	s_waitcnt vmcnt(0)
	v_pk_mul_f32 v[30:31], v[46:47], v[30:31]
	v_pk_mul_f32 v[32:33], v[48:49], v[32:33]
	v_cvt_pk_bf16_f32 v30, v30, v31
	v_cvt_pk_bf16_f32 v31, v32, v33
	v_pk_mul_f32 v[32:33], v[54:55], v[52:53] op_sel_hi:[1,0]
	v_pk_mul_f32 v[34:35], v[34:35], v[52:53] op_sel_hi:[1,0]
	v_pk_mul_f32 v[32:33], v[42:43], v[32:33]
	v_pk_mul_f32 v[34:35], v[44:45], v[34:35]
	v_cvt_pk_bf16_f32 v32, v32, v33
	v_cvt_pk_bf16_f32 v33, v34, v35
	s_andn2_b64 vcc, exec, s[6:7]
	global_store_dwordx4 v[50:51], v[30:33], off
	s_cbranch_vccnz .LBB0_131
; __device__ __forceinline__ unsigned cvt_pk_bf16(float lo, float hi) { f32x2 v = {lo, hi}; bf16x2_t b = __builtin_convertvector(v, bf16x2_t); return __builtin_bit_cast(unsigned, b); }
; __device__ __forceinline__ float bflo(unsigned w) { return __uint_as_float(w << 16); }
; __device__ __forceinline__ float bfhi(unsigned w) { return __uint_as_float(w & 0xffff0000u); }
; __device__ __forceinline__ float silu_f(float g) { return g * __builtin_amdgcn_rcpf(1.0f + __expf(-g)); }
; __device__ __forceinline__ void gate_phase(const Ctx& c) {
;     ...
;         for (int u = 0; u < U; ++u) {
;             const int it = it0 + u * c.ngw;
;             if (it < NIT) {
;                 const int row = it >> 2, col = (it & 3) * 512 + c.lane * 8;
;                 float y[8] = {bflo(yv[u].x), bfhi(yv[u].x), bflo(yv[u].y), bfhi(yv[u].y), bflo(yv[u].z), bfhi(yv[u].z), bflo(yv[u].w), bfhi(yv[u].w)};
;                 const float z[8] = {bflo(zv[u].x), bfhi(zv[u].x), bflo(zv[u].y), bfhi(zv[u].y), bflo(zv[u].z), bfhi(zv[u].z), bflo(zv[u].w), bfhi(zv[u].w)};
;                 float ss = 0.f;
; #pragma unroll
;                 for (int j = 0; j < 8; ++j) { y[j] *= silu_f(z[j]); ss += y[j] * y[j]; }
;                 const float rs = rsqrtf(wave_sum(ss) * (1.0f / 512.0f) + EPS);
;                 const f32x4 n0 = *(const f32x4*)(nw + col), n1 = *(const f32x4*)(nw + col + 4);
;                 u32x4 o; o.x = cvt_pk_bf16(y[0] * rs * n0[0], y[1] * rs * n0[1]); o.y = cvt_pk_bf16(y[2] * rs * n0[2], y[3] * rs * n0[3]);
;                 o.z = cvt_pk_bf16(y[4] * rs * n1[0], y[5] * rs * n1[1]); o.w = cvt_pk_bf16(y[6] * rs * n1[2], y[7] * rs * n1[3]);
;                 *(u32x4*)(Z + (size_t)row * DIN + col) = o;
	v_lshlrev_b32_e32 v34, 16, v27
	v_and_b32_e32 v35, 0xffff0000, v27
	v_mul_f32_e32 v1, 0xbfb8aa3b, v34
	v_exp_f32_e32 v1, v1
	v_mul_f32_e32 v27, 0xbfb8aa3b, v35
	v_exp_f32_e32 v27, v27
	v_lshlrev_b32_e32 v48, 16, v23
	v_add_f32_e32 v1, 1.0, v1
	v_rcp_f32_e32 v46, v1
	v_add_f32_e32 v1, 1.0, v27
	v_rcp_f32_e32 v47, v1
	v_and_b32_e32 v49, 0xffff0000, v23
	global_load_dwordx4 v[30:33], v[28:29], off offset:16
	global_load_dwordx4 v[42:45], v[28:29], off
	v_lshlrev_b32_e32 v50, 16, v22
	v_pk_mul_f32 v[34:35], v[46:47], v[34:35]
	v_lshlrev_b32_e32 v46, 16, v26
	v_and_b32_e32 v47, 0xffff0000, v26
	v_mul_f32_e32 v1, 0xbfb8aa3b, v46
	v_exp_f32_e32 v1, v1
	v_mul_f32_e32 v23, 0xbfb8aa3b, v47
	v_exp_f32_e32 v23, v23
	v_pk_mul_f32 v[26:27], v[34:35], v[48:49]
	v_add_f32_e32 v1, 1.0, v1
	v_rcp_f32_e32 v34, v1
	v_add_f32_e32 v1, 1.0, v23
	v_rcp_f32_e32 v35, v1
	v_and_b32_e32 v51, 0xffff0000, v22
	v_lshlrev_b32_e32 v52, 16, v21
	v_and_b32_e32 v53, 0xffff0000, v21
	v_pk_mul_f32 v[22:23], v[34:35], v[46:47]
	v_lshlrev_b32_e32 v34, 16, v25
	v_and_b32_e32 v35, 0xffff0000, v25
	v_mul_f32_e32 v1, 0xbfb8aa3b, v34
	v_exp_f32_e32 v1, v1
	v_mul_f32_e32 v25, 0xbfb8aa3b, v35
	v_exp_f32_e32 v25, v25
	v_lshlrev_b32_e32 v54, 16, v20
	v_add_f32_e32 v1, 1.0, v1
	v_rcp_f32_e32 v46, v1
	v_add_f32_e32 v1, 1.0, v25
	v_rcp_f32_e32 v47, v1
	v_and_b32_e32 v55, 0xffff0000, v20
	v_pk_mul_f32 v[22:23], v[22:23], v[50:51]
	v_pk_mul_f32 v[48:49], v[26:27], v[26:27]
	v_pk_mul_f32 v[34:35], v[46:47], v[34:35]
	v_lshlrev_b32_e32 v46, 16, v24
	v_and_b32_e32 v47, 0xffff0000, v24
	v_mul_f32_e32 v1, 0xbfb8aa3b, v46
	v_exp_f32_e32 v1, v1
	v_mul_f32_e32 v21, 0xbfb8aa3b, v47
	v_exp_f32_e32 v21, v21
	v_pk_mul_f32 v[24:25], v[34:35], v[52:53]
	v_add_f32_e32 v1, 1.0, v1
	v_rcp_f32_e32 v34, v1
	v_add_f32_e32 v1, 1.0, v21
	v_rcp_f32_e32 v35, v1
	v_pk_mul_f32 v[52:53], v[24:25], v[24:25]
	v_pk_mul_f32 v[50:51], v[22:23], v[22:23]
	s_ashr_i32 s6, s17, 2
	v_pk_mul_f32 v[20:21], v[34:35], v[46:47]
	s_ashr_i32 s7, s6, 31
	v_pk_mul_f32 v[20:21], v[20:21], v[54:55]
	s_lshl_b64 s[6:7], s[6:7], 12
	v_pk_mul_f32 v[34:35], v[20:21], v[20:21]
	s_add_u32 s6, s14, s6
	v_add_f32_e32 v1, v34, v35
	v_add_f32_e32 v1, v52, v1
	v_add_f32_e32 v1, v53, v1
	v_add_f32_e32 v1, v50, v1
	v_add_f32_e32 v1, v51, v1
	v_add_f32_e32 v1, v48, v1
	v_add_f32_e32 v1, v49, v1
	s_nop 1
	v_add_f32_dpp v1, v1, v1 quad_perm:[1,0,3,2] row_mask:0xf bank_mask:0xf
	s_nop 1
	v_add_f32_dpp v1, v1, v1 quad_perm:[2,3,0,1] row_mask:0xf bank_mask:0xf
	s_nop 1
	v_add_f32_dpp v1, v1, v1 row_half_mirror row_mask:0xf bank_mask:0xf
	s_nop 1
	v_add_f32_dpp v1, v1, v1 row_mirror row_mask:0xf bank_mask:0xf
	s_nop 1
	v_add_f32_dpp v1, v1, v1 row_bcast:15 row_mask:0xa bank_mask:0xf
	s_nop 1
	v_add_f32_dpp v1, v1, v1 row_bcast:31 row_mask:0xc bank_mask:0xf
	s_nop 0
	v_readlane_b32 s32, v1, 63
	s_nop 1
	v_mov_b32_e32 v1, s32
	s_addc_u32 s7, s15, s7
	v_fmamk_f32 v1, v1, 0x3b000000, v228
	v_mul_f32_e32 v34, 0x4b800000, v1
	v_cmp_gt_f32_e32 vcc, s37, v1
	s_nop 1
	v_cndmask_b32_e32 v1, v1, v34, vcc
	v_rsq_f32_e32 v1, v1
	s_nop 0
	v_mul_f32_e32 v34, 0x45800000, v1
	v_cndmask_b32_e32 v34, v1, v34, vcc
	v_pk_mul_f32 v[20:21], v[20:21], v[34:35] op_sel_hi:[1,0]
	v_pk_mul_f32 v[24:25], v[24:25], v[34:35] op_sel_hi:[1,0]
	s_waitcnt vmcnt(0)
	v_pk_mul_f32 v[20:21], v[42:43], v[20:21]
	v_pk_mul_f32 v[24:25], v[44:45], v[24:25]
	v_cvt_pk_bf16_f32 v20, v20, v21
	v_cvt_pk_bf16_f32 v21, v24, v25
	v_pk_mul_f32 v[22:23], v[22:23], v[34:35] op_sel_hi:[1,0]
	v_pk_mul_f32 v[24:25], v[26:27], v[34:35] op_sel_hi:[1,0]
	v_pk_mul_f32 v[22:23], v[30:31], v[22:23]
	v_pk_mul_f32 v[24:25], v[32:33], v[24:25]
	v_cvt_pk_bf16_f32 v22, v22, v23
	v_cvt_pk_bf16_f32 v23, v24, v25
	global_store_dwordx4 v0, v[20:23], s[6:7]
	s_andn2_b64 vcc, exec, s[4:5]
	s_cbranch_vccz .LBB0_132

; __device__ __forceinline__ unsigned cvt_pk_bf16(float lo, float hi) { f32x2 v = {lo, hi}; bf16x2_t b = __builtin_convertvector(v, bf16x2_t); return __builtin_bit_cast(unsigned, b); }
; __device__ __forceinline__ float bflo(unsigned w) { return __uint_as_float(w << 16); }
; __device__ __forceinline__ float bfhi(unsigned w) { return __uint_as_float(w & 0xffff0000u); }
; __device__ __forceinline__ float silu_f(float g) { return g * __builtin_amdgcn_rcpf(1.0f + __expf(-g)); }
; __device__ __forceinline__ void gate_phase(const Ctx& c) {
;     ...
;         for (int u = 0; u < U; ++u) {
;             const int it = it0 + u * c.ngw;
;             if (it < NIT) {
;                 const int row = it >> 2, col = (it & 3) * 512 + c.lane * 8;
;                 float y[8] = {bflo(yv[u].x), bfhi(yv[u].x), bflo(yv[u].y), bfhi(yv[u].y), bflo(yv[u].z), bfhi(yv[u].z), bflo(yv[u].w), bfhi(yv[u].w)};
;                 const float z[8] = {bflo(zv[u].x), bfhi(zv[u].x), bflo(zv[u].y), bfhi(zv[u].y), bflo(zv[u].z), bfhi(zv[u].z), bflo(zv[u].w), bfhi(zv[u].w)};
;                 float ss = 0.f;
; #pragma unroll
;                 for (int j = 0; j < 8; ++j) { y[j] *= silu_f(z[j]); ss += y[j] * y[j]; }
;                 const float rs = rsqrtf(wave_sum(ss) * (1.0f / 512.0f) + EPS);
;                 const f32x4 n0 = *(const f32x4*)(nw + col), n1 = *(const f32x4*)(nw + col + 4);
;                 u32x4 o; o.x = cvt_pk_bf16(y[0] * rs * n0[0], y[1] * rs * n0[1]); o.y = cvt_pk_bf16(y[2] * rs * n0[2], y[3] * rs * n0[3]);
;                 o.z = cvt_pk_bf16(y[4] * rs * n1[0], y[5] * rs * n1[1]); o.w = cvt_pk_bf16(y[6] * rs * n1[2], y[7] * rs * n1[3]);
;                 *(u32x4*)(Z + (size_t)row * DIN + col) = o;
.LBB0_132:
	v_lshlrev_b32_e32 v30, 16, v19
	v_and_b32_e32 v31, 0xffff0000, v19
	v_mul_f32_e32 v1, 0xbfb8aa3b, v30
	v_exp_f32_e32 v1, v1
	v_mul_f32_e32 v19, 0xbfb8aa3b, v31
	v_exp_f32_e32 v19, v19
	v_lshlrev_b32_e32 v34, 16, v15
	v_add_f32_e32 v1, 1.0, v1
	v_rcp_f32_e32 v32, v1
	v_add_f32_e32 v1, 1.0, v19
	v_rcp_f32_e32 v33, v1
	v_and_b32_e32 v35, 0xffff0000, v15
	global_load_dwordx4 v[20:23], v[28:29], off offset:16
	global_load_dwordx4 v[24:27], v[28:29], off
	v_lshlrev_b32_e32 v42, 16, v14
	v_pk_mul_f32 v[30:31], v[32:33], v[30:31]
	v_lshlrev_b32_e32 v32, 16, v18
	v_and_b32_e32 v33, 0xffff0000, v18
	v_mul_f32_e32 v1, 0xbfb8aa3b, v32
	v_exp_f32_e32 v1, v1
	v_mul_f32_e32 v15, 0xbfb8aa3b, v33
	v_exp_f32_e32 v15, v15
	v_pk_mul_f32 v[18:19], v[30:31], v[34:35]
	v_add_f32_e32 v1, 1.0, v1
	v_rcp_f32_e32 v30, v1
	v_add_f32_e32 v1, 1.0, v15
	v_rcp_f32_e32 v31, v1
	v_and_b32_e32 v43, 0xffff0000, v14
	v_lshlrev_b32_e32 v44, 16, v13
	v_and_b32_e32 v45, 0xffff0000, v13
	v_pk_mul_f32 v[14:15], v[30:31], v[32:33]
	v_lshlrev_b32_e32 v30, 16, v17
	v_and_b32_e32 v31, 0xffff0000, v17
	v_mul_f32_e32 v1, 0xbfb8aa3b, v30
	v_exp_f32_e32 v1, v1
	v_mul_f32_e32 v17, 0xbfb8aa3b, v31
	v_exp_f32_e32 v17, v17
	v_lshlrev_b32_e32 v46, 16, v12
	v_add_f32_e32 v1, 1.0, v1
	v_rcp_f32_e32 v32, v1
	v_add_f32_e32 v1, 1.0, v17
	v_rcp_f32_e32 v33, v1
	v_and_b32_e32 v47, 0xffff0000, v12
	v_pk_mul_f32 v[14:15], v[14:15], v[42:43]
	v_pk_mul_f32 v[34:35], v[18:19], v[18:19]
	v_pk_mul_f32 v[30:31], v[32:33], v[30:31]
	v_lshlrev_b32_e32 v32, 16, v16
	v_and_b32_e32 v33, 0xffff0000, v16
	v_mul_f32_e32 v1, 0xbfb8aa3b, v32
	v_exp_f32_e32 v1, v1
	v_mul_f32_e32 v13, 0xbfb8aa3b, v33
	v_exp_f32_e32 v13, v13
	v_pk_mul_f32 v[16:17], v[30:31], v[44:45]
	v_add_f32_e32 v1, 1.0, v1
	v_rcp_f32_e32 v30, v1
	v_add_f32_e32 v1, 1.0, v13
	v_rcp_f32_e32 v31, v1
	v_pk_mul_f32 v[44:45], v[16:17], v[16:17]
	v_pk_mul_f32 v[42:43], v[14:15], v[14:15]
	s_ashr_i32 s4, s19, 2
	v_pk_mul_f32 v[12:13], v[30:31], v[32:33]
	s_ashr_i32 s5, s4, 31
	v_pk_mul_f32 v[12:13], v[12:13], v[46:47]
	s_lshl_b64 s[4:5], s[4:5], 12
	v_pk_mul_f32 v[30:31], v[12:13], v[12:13]
	s_add_u32 s4, s14, s4
	v_add_f32_e32 v1, v30, v31
	v_add_f32_e32 v1, v44, v1
	v_add_f32_e32 v1, v45, v1
	v_add_f32_e32 v1, v42, v1
	v_add_f32_e32 v1, v43, v1
	v_add_f32_e32 v1, v34, v1
	v_add_f32_e32 v1, v35, v1
	s_nop 1
	v_add_f32_dpp v1, v1, v1 quad_perm:[1,0,3,2] row_mask:0xf bank_mask:0xf
	s_nop 1
	v_add_f32_dpp v1, v1, v1 quad_perm:[2,3,0,1] row_mask:0xf bank_mask:0xf
	s_nop 1
	v_add_f32_dpp v1, v1, v1 row_half_mirror row_mask:0xf bank_mask:0xf
	s_nop 1
	v_add_f32_dpp v1, v1, v1 row_mirror row_mask:0xf bank_mask:0xf
	s_nop 1
	v_add_f32_dpp v1, v1, v1 row_bcast:15 row_mask:0xa bank_mask:0xf
	s_nop 1
	v_add_f32_dpp v1, v1, v1 row_bcast:31 row_mask:0xc bank_mask:0xf
	s_nop 0
	v_readlane_b32 s32, v1, 63
	s_nop 1
	v_mov_b32_e32 v1, s32
	s_addc_u32 s5, s15, s5
	v_fmamk_f32 v1, v1, 0x3b000000, v228
	v_mul_f32_e32 v30, 0x4b800000, v1
	v_cmp_gt_f32_e32 vcc, s37, v1
	s_nop 1
	v_cndmask_b32_e32 v1, v1, v30, vcc
	v_rsq_f32_e32 v1, v1
	s_nop 0
	v_mul_f32_e32 v30, 0x45800000, v1
	v_cndmask_b32_e32 v30, v1, v30, vcc
	v_pk_mul_f32 v[12:13], v[12:13], v[30:31] op_sel_hi:[1,0]
	v_pk_mul_f32 v[16:17], v[16:17], v[30:31] op_sel_hi:[1,0]
	s_waitcnt vmcnt(0)
	v_pk_mul_f32 v[12:13], v[24:25], v[12:13]
	v_pk_mul_f32 v[16:17], v[26:27], v[16:17]
	v_cvt_pk_bf16_f32 v12, v12, v13
	v_cvt_pk_bf16_f32 v13, v16, v17
	v_pk_mul_f32 v[14:15], v[14:15], v[30:31] op_sel_hi:[1,0]
	v_pk_mul_f32 v[16:17], v[18:19], v[30:31] op_sel_hi:[1,0]
	v_pk_mul_f32 v[14:15], v[20:21], v[14:15]
	v_pk_mul_f32 v[16:17], v[22:23], v[16:17]
	v_cvt_pk_bf16_f32 v14, v14, v15
	v_cvt_pk_bf16_f32 v15, v16, v17
	global_store_dwordx4 v0, v[12:15], s[4:5]
	s_andn2_b64 vcc, exec, s[2:3]
	s_cbranch_vccnz .LBB0_115
; __device__ __forceinline__ unsigned cvt_pk_bf16(float lo, float hi) { f32x2 v = {lo, hi}; bf16x2_t b = __builtin_convertvector(v, bf16x2_t); return __builtin_bit_cast(unsigned, b); }
; __device__ __forceinline__ float bflo(unsigned w) { return __uint_as_float(w << 16); }
; __device__ __forceinline__ float bfhi(unsigned w) { return __uint_as_float(w & 0xffff0000u); }
; __device__ __forceinline__ float silu_f(float g) { return g * __builtin_amdgcn_rcpf(1.0f + __expf(-g)); }
; __device__ __forceinline__ void gate_phase(const Ctx& c) {
;     ...
;         for (int u = 0; u < U; ++u) {
;             const int it = it0 + u * c.ngw;
;             if (it < NIT) {
;                 const int row = it >> 2, col = (it & 3) * 512 + c.lane * 8;
;                 float y[8] = {bflo(yv[u].x), bfhi(yv[u].x), bflo(yv[u].y), bfhi(yv[u].y), bflo(yv[u].z), bfhi(yv[u].z), bflo(yv[u].w), bfhi(yv[u].w)};
;                 const float z[8] = {bflo(zv[u].x), bfhi(zv[u].x), bflo(zv[u].y), bfhi(zv[u].y), bflo(zv[u].z), bfhi(zv[u].z), bflo(zv[u].w), bfhi(zv[u].w)};
;                 float ss = 0.f;
; #pragma unroll
;                 for (int j = 0; j < 8; ++j) { y[j] *= silu_f(z[j]); ss += y[j] * y[j]; }
;                 const float rs = rsqrtf(wave_sum(ss) * (1.0f / 512.0f) + EPS);
;                 const f32x4 n0 = *(const f32x4*)(nw + col), n1 = *(const f32x4*)(nw + col + 4);
;                 u32x4 o; o.x = cvt_pk_bf16(y[0] * rs * n0[0], y[1] * rs * n0[1]); o.y = cvt_pk_bf16(y[2] * rs * n0[2], y[3] * rs * n0[3]);
;                 o.z = cvt_pk_bf16(y[4] * rs * n1[0], y[5] * rs * n1[1]); o.w = cvt_pk_bf16(y[6] * rs * n1[2], y[7] * rs * n1[3]);
;                 *(u32x4*)(Z + (size_t)row * DIN + col) = o;
.LBB0_133:
	v_lshlrev_b32_e32 v20, 16, v11
	v_and_b32_e32 v21, 0xffff0000, v11
	v_mul_f32_e32 v1, 0xbfb8aa3b, v20
	v_exp_f32_e32 v1, v1
	v_mul_f32_e32 v11, 0xbfb8aa3b, v21
	v_exp_f32_e32 v11, v11
	v_lshlrev_b32_e32 v24, 16, v7
	v_add_f32_e32 v1, 1.0, v1
	v_rcp_f32_e32 v22, v1
	v_add_f32_e32 v1, 1.0, v11
	v_rcp_f32_e32 v23, v1
	v_and_b32_e32 v25, 0xffff0000, v7
	global_load_dwordx4 v[12:15], v[28:29], off offset:16
	global_load_dwordx4 v[16:19], v[28:29], off
	v_lshlrev_b32_e32 v26, 16, v6
	v_pk_mul_f32 v[20:21], v[22:23], v[20:21]
	v_lshlrev_b32_e32 v22, 16, v10
	v_and_b32_e32 v23, 0xffff0000, v10
	v_mul_f32_e32 v1, 0xbfb8aa3b, v22
	v_exp_f32_e32 v1, v1
	v_mul_f32_e32 v7, 0xbfb8aa3b, v23
	v_exp_f32_e32 v7, v7
	v_pk_mul_f32 v[10:11], v[20:21], v[24:25]
	v_add_f32_e32 v1, 1.0, v1
	v_rcp_f32_e32 v20, v1
	v_add_f32_e32 v1, 1.0, v7
	v_rcp_f32_e32 v21, v1
	v_and_b32_e32 v27, 0xffff0000, v6
	v_lshlrev_b32_e32 v28, 16, v5
	v_and_b32_e32 v29, 0xffff0000, v5
	v_pk_mul_f32 v[6:7], v[20:21], v[22:23]
	v_lshlrev_b32_e32 v20, 16, v9
	v_and_b32_e32 v21, 0xffff0000, v9
	v_mul_f32_e32 v1, 0xbfb8aa3b, v20
	v_exp_f32_e32 v1, v1
	v_mul_f32_e32 v9, 0xbfb8aa3b, v21
	v_exp_f32_e32 v9, v9
	v_lshlrev_b32_e32 v30, 16, v4
	v_add_f32_e32 v1, 1.0, v1
	v_rcp_f32_e32 v22, v1
	v_add_f32_e32 v1, 1.0, v9
	v_rcp_f32_e32 v23, v1
	v_and_b32_e32 v31, 0xffff0000, v4
	v_pk_mul_f32 v[6:7], v[6:7], v[26:27]
	v_pk_mul_f32 v[24:25], v[10:11], v[10:11]
	v_pk_mul_f32 v[20:21], v[22:23], v[20:21]
	v_lshlrev_b32_e32 v22, 16, v8
	v_and_b32_e32 v23, 0xffff0000, v8
	v_mul_f32_e32 v1, 0xbfb8aa3b, v22
	v_exp_f32_e32 v1, v1
	v_mul_f32_e32 v5, 0xbfb8aa3b, v23
	v_exp_f32_e32 v5, v5
	v_pk_mul_f32 v[8:9], v[20:21], v[28:29]
	v_add_f32_e32 v1, 1.0, v1
	v_rcp_f32_e32 v20, v1
	v_add_f32_e32 v1, 1.0, v5
	v_rcp_f32_e32 v21, v1
	v_pk_mul_f32 v[28:29], v[8:9], v[8:9]
	v_pk_mul_f32 v[26:27], v[6:7], v[6:7]
	s_ashr_i32 s2, s18, 2
	v_pk_mul_f32 v[4:5], v[20:21], v[22:23]
	s_ashr_i32 s3, s2, 31
	v_pk_mul_f32 v[4:5], v[4:5], v[30:31]
	s_lshl_b64 s[2:3], s[2:3], 12
	v_pk_mul_f32 v[20:21], v[4:5], v[4:5]
	s_add_u32 s2, s14, s2
	v_add_f32_e32 v1, v20, v21
	v_add_f32_e32 v1, v28, v1
	v_add_f32_e32 v1, v29, v1
	v_add_f32_e32 v1, v26, v1
	v_add_f32_e32 v1, v27, v1
	v_add_f32_e32 v1, v24, v1
	v_add_f32_e32 v1, v25, v1
	s_nop 1
	v_add_f32_dpp v1, v1, v1 quad_perm:[1,0,3,2] row_mask:0xf bank_mask:0xf
	s_nop 1
	v_add_f32_dpp v1, v1, v1 quad_perm:[2,3,0,1] row_mask:0xf bank_mask:0xf
	s_nop 1
	v_add_f32_dpp v1, v1, v1 row_half_mirror row_mask:0xf bank_mask:0xf
	s_nop 1
	v_add_f32_dpp v1, v1, v1 row_mirror row_mask:0xf bank_mask:0xf
	s_nop 1
	v_add_f32_dpp v1, v1, v1 row_bcast:15 row_mask:0xa bank_mask:0xf
	s_nop 1
	v_add_f32_dpp v1, v1, v1 row_bcast:31 row_mask:0xc bank_mask:0xf
	s_nop 0
	v_readlane_b32 s32, v1, 63
	s_nop 1
	v_mov_b32_e32 v1, s32
	s_addc_u32 s3, s15, s3
	v_fmamk_f32 v1, v1, 0x3b000000, v228
	v_mul_f32_e32 v20, 0x4b800000, v1
	v_cmp_gt_f32_e32 vcc, s37, v1
	s_nop 1
	v_cndmask_b32_e32 v1, v1, v20, vcc
	v_rsq_f32_e32 v1, v1
	s_nop 0
	v_mul_f32_e32 v20, 0x45800000, v1
	v_cndmask_b32_e32 v20, v1, v20, vcc
	v_pk_mul_f32 v[4:5], v[4:5], v[20:21] op_sel_hi:[1,0]
	v_pk_mul_f32 v[8:9], v[8:9], v[20:21] op_sel_hi:[1,0]
	s_waitcnt vmcnt(0)
	v_pk_mul_f32 v[4:5], v[16:17], v[4:5]
	v_pk_mul_f32 v[8:9], v[18:19], v[8:9]
	v_cvt_pk_bf16_f32 v4, v4, v5
	v_cvt_pk_bf16_f32 v5, v8, v9
	v_pk_mul_f32 v[6:7], v[6:7], v[20:21] op_sel_hi:[1,0]
	v_pk_mul_f32 v[8:9], v[10:11], v[20:21] op_sel_hi:[1,0]
	v_pk_mul_f32 v[6:7], v[12:13], v[6:7]
	v_pk_mul_f32 v[8:9], v[14:15], v[8:9]
	v_cvt_pk_bf16_f32 v6, v6, v7
	v_cvt_pk_bf16_f32 v7, v8, v9
	global_store_dwordx4 v0, v[4:7], s[2:3]
	s_branch .LBB0_115

; __device__ __forceinline__ float bflo(unsigned w) { return __uint_as_float(w << 16); }
; __device__ __forceinline__ float bfhi(unsigned w) { return __uint_as_float(w & 0xffff0000u); }
; __device__ __forceinline__ void norm_phase(const Ctx& c, int s) {
;     ...
;                     for (int j = 0; j < 4; ++j) { v[j] = xf32 ? cu[k].v[j] : (f32x4){bflo(cu[k].xb[j].x), bfhi(cu[k].xb[j].x), bflo(cu[k].xb[j].y), bfhi(cu[k].xb[j].y)};
;                         fv[j] = (f32x4){bflo(cu[k].f[j].x), bfhi(cu[k].f[j].x), bflo(cu[k].f[j].y), bfhi(cu[k].f[j].y)}; }
;                     if (has_upd) { float p = cu[k].p; p += __shfl_xor(p, 1); p += __shfl_xor(p, 2); p += __shfl_xor(p, 4); p += __shfl_xor(p, 8); rf = rsqrtf(p * (1.0f / D) + EPS); }
;                     NORM_BODY(row, v, fv, rf);
.LBB0_675:
	v_lshlrev_b32_e32 v119, 16, v226
	v_and_b32_e32 v121, 0xffff0000, v226
	v_lshlrev_b32_e32 v148, 16, v227
	v_and_b32_e32 v149, 0xffff0000, v227
	v_cndmask_b32_e64 v115, v115, v149, s[2:3]
	v_cndmask_b32_e64 v114, v114, v148, s[2:3]
	v_cndmask_b32_e64 v113, v113, v121, s[2:3]
	v_cndmask_b32_e64 v112, v112, v119, s[2:3]
	v_lshlrev_b32_e32 v119, 16, v224
	v_and_b32_e32 v121, 0xffff0000, v224
	v_lshlrev_b32_e32 v148, 16, v225
	v_and_b32_e32 v149, 0xffff0000, v225
	v_cndmask_b32_e64 v111, v111, v149, s[2:3]
	v_cndmask_b32_e64 v110, v110, v148, s[2:3]
	v_cndmask_b32_e64 v109, v109, v121, s[2:3]
	v_cndmask_b32_e64 v108, v108, v119, s[2:3]
	v_lshlrev_b32_e32 v119, 16, v222
	v_and_b32_e32 v121, 0xffff0000, v222
	v_lshlrev_b32_e32 v148, 16, v223
	v_and_b32_e32 v149, 0xffff0000, v223
	v_cndmask_b32_e64 v107, v107, v149, s[2:3]
	v_cndmask_b32_e64 v106, v106, v148, s[2:3]
	v_cndmask_b32_e64 v105, v105, v121, s[2:3]
	v_cndmask_b32_e64 v104, v104, v119, s[2:3]
	v_lshlrev_b32_e32 v119, 16, v220
	v_and_b32_e32 v121, 0xffff0000, v220
	v_lshlrev_b32_e32 v148, 16, v221
	v_and_b32_e32 v149, 0xffff0000, v221
	v_cndmask_b32_e64 v103, v103, v149, s[2:3]
	v_cndmask_b32_e64 v102, v102, v148, s[2:3]
	v_cndmask_b32_e64 v101, v101, v121, s[2:3]
	s_and_b64 vcc, exec, s[4:5]
	v_cndmask_b32_e64 v100, v100, v119, s[2:3]
	s_cbranch_vccnz .LBB0_692
	v_lshlrev_b32_e32 v220, 16, v218
	s_nop 1
	v_add_f32_dpp v119, v125, v125 quad_perm:[1,0,3,2] row_mask:0xf bank_mask:0xf
	s_nop 1
	v_add_f32_dpp v119, v119, v119 quad_perm:[2,3,0,1] row_mask:0xf bank_mask:0xf
	s_nop 1
	v_add_f32_dpp v119, v119, v119 row_half_mirror row_mask:0xf bank_mask:0xf
	s_nop 1
	v_add_f32_dpp v119, v119, v119 row_mirror row_mask:0xf bank_mask:0xf
	v_and_b32_e32 v221, 0xffff0000, v218
	v_lshlrev_b32_e32 v222, 16, v219
	v_and_b32_e32 v223, 0xffff0000, v219
	v_pk_mul_f32 v[220:221], v[36:37], v[220:221]
	v_pk_mul_f32 v[222:223], v[38:39], v[222:223]
	s_mov_b64 s[6:7], -1
	v_fmamk_f32 v119, v119, 0x3a800000, v228
	v_mul_f32_e32 v121, 0x4b800000, v119
	v_cmp_gt_f32_e32 vcc, s62, v119
	s_nop 1
	v_cndmask_b32_e32 v119, v119, v121, vcc
	v_rsq_f32_e32 v119, v119
	s_nop 0
	v_mul_f32_e32 v121, 0x45800000, v119
	v_cndmask_b32_e32 v218, v119, v121, vcc
	v_pk_fma_f32 v[114:115], v[222:223], v[218:219], v[114:115] op_sel_hi:[1,0,1]
	v_pk_fma_f32 v[112:113], v[220:221], v[218:219], v[112:113] op_sel_hi:[1,0,1]
	s_andn2_b64 vcc, exec, s[12:13]
	v_lshl_add_u64 v[220:221], s[38:39], 0, v[138:139]
	s_cbranch_vccnz .LBB0_678
	v_cvt_pk_bf16_f32 v222, v112, v113
	v_cvt_pk_bf16_f32 v223, v114, v115
	s_mov_b64 s[6:7], 0
	global_store_dwordx2 v[220:221], v[222:223], off

; __device__ __forceinline__ float wave_sum(float v) {
; #pragma unroll
;     for (int o = 1; o < 64; o <<= 1) v += __shfl_xor(v, o);
;     return v;
; }
.LBB0_692:
	v_cndmask_b32_e64 v119, 0, 1, s[12:13]
	v_cmp_ne_u32_e64 s[6:7], 1, v119
	s_andn2_b64 vcc, exec, s[12:13]
	s_cbranch_vccnz .LBB0_694
	v_pk_mul_f32 v[212:213], v[114:115], v[114:115]
	v_pk_mul_f32 v[214:215], v[112:113], v[112:113]
	v_pk_mov_b32 v[216:217], v[214:215], v[212:213] op_sel:[1,0]
	v_mov_b32_e32 v215, v213
	v_pk_add_f32 v[212:213], v[216:217], v[214:215]
	v_pk_mul_f32 v[214:215], v[110:111], v[110:111]
	v_pk_add_f32 v[212:213], v[212:213], v[212:213] op_sel_hi:[0,1]
	v_pk_mul_f32 v[216:217], v[108:109], v[108:109]
	v_mul_f32_e32 v212, v104, v104
	v_pk_mov_b32 v[218:219], v[216:217], v[214:215] op_sel:[1,0]
	v_mov_b32_e32 v217, v215
	v_pk_add_f32 v[214:215], v[218:219], v[216:217]
	v_pk_fma_f32 v[216:217], v[104:105], v[104:105], v[212:213] op_sel_hi:[1,1,0]
	v_mul_f32_e32 v212, v106, v106
	v_pk_add_f32 v[214:215], v[214:215], v[214:215] op_sel_hi:[0,1]
	v_pk_fma_f32 v[218:219], v[106:107], v[106:107], v[212:213] op_sel_hi:[1,1,0]
	v_mul_f32_e32 v216, v100, v100
	v_mul_f32_e32 v218, v101, v101
	v_mul_f32_e32 v214, v102, v102
	v_mul_f32_e32 v212, v103, v103
	v_pk_add_f32 v[216:217], v[216:217], v[218:219]
	v_pk_add_f32 v[212:213], v[214:215], v[212:213]
	v_pk_add_f32 v[212:213], v[216:217], v[212:213]
	v_pk_mul_f32 v[114:115], v[22:23], v[114:115]
	v_add_f32_e32 v119, v212, v213
	s_nop 1
	v_add_f32_dpp v119, v119, v119 quad_perm:[1,0,3,2] row_mask:0xf bank_mask:0xf
	s_nop 1
	v_add_f32_dpp v119, v119, v119 quad_perm:[2,3,0,1] row_mask:0xf bank_mask:0xf
	s_nop 1
	v_add_f32_dpp v119, v119, v119 row_half_mirror row_mask:0xf bank_mask:0xf
	s_nop 1
	v_add_f32_dpp v119, v119, v119 row_mirror row_mask:0xf bank_mask:0xf
	s_nop 1
	v_add_f32_dpp v119, v119, v119 row_bcast:15 row_mask:0xa bank_mask:0xf
	s_nop 1
	v_add_f32_dpp v119, v119, v119 row_bcast:31 row_mask:0xc bank_mask:0xf
	s_nop 0
	v_readlane_b32 s32, v119, 63
	s_nop 1
	v_mov_b32_e32 v119, s32
	v_pk_mul_f32 v[112:113], v[20:21], v[112:113]
	s_mov_b32 s43, 0x6e88000
	v_pk_mul_f32 v[110:111], v[30:31], v[110:111]
	v_pk_mul_f32 v[108:109], v[28:29], v[108:109]
	v_pk_mul_f32 v[106:107], v[26:27], v[106:107]
	v_pk_mul_f32 v[104:105], v[24:25], v[104:105]
	v_pk_mul_f32 v[102:103], v[34:35], v[102:103]
	v_pk_mul_f32 v[100:101], v[32:33], v[100:101]
	v_fmamk_f32 v119, v119, 0x3a800000, v228
	v_mul_f32_e32 v121, 0x4b800000, v119
	v_cmp_gt_f32_e32 vcc, s62, v119
	s_nop 1
	v_cndmask_b32_e32 v119, v119, v121, vcc
	v_rsq_f32_e32 v119, v119
	s_nop 0
	v_mul_f32_e32 v121, 0x45800000, v119
	v_cndmask_b32_e32 v212, v119, v121, vcc
	s_waitcnt vmcnt(0)
	v_pk_fma_f32 v[114:115], v[114:115], v[212:213], v[6:7] op_sel_hi:[1,0,1]
	v_pk_fma_f32 v[112:113], v[112:113], v[212:213], v[4:5] op_sel_hi:[1,0,1]
	v_pk_fma_f32 v[110:111], v[110:111], v[212:213], v[14:15] op_sel_hi:[1,0,1]
	v_cvt_pk_bf16_f32 v112, v112, v113
	v_cvt_pk_bf16_f32 v113, v114, v115
	v_lshl_add_u64 v[114:115], s[26:27], 0, v[138:139]
	v_add_co_u32_e32 v114, vcc, s43, v114
	v_pk_fma_f32 v[108:109], v[108:109], v[212:213], v[12:13] op_sel_hi:[1,0,1]
	v_pk_fma_f32 v[106:107], v[106:107], v[212:213], v[10:11] op_sel_hi:[1,0,1]
	v_pk_fma_f32 v[104:105], v[104:105], v[212:213], v[8:9] op_sel_hi:[1,0,1]
	v_pk_fma_f32 v[102:103], v[102:103], v[212:213], v[18:19] op_sel_hi:[1,0,1]
	v_pk_fma_f32 v[100:101], v[100:101], v[212:213], v[16:17] op_sel_hi:[1,0,1]
	v_addc_co_u32_e32 v115, vcc, 0, v115, vcc
	v_cvt_pk_bf16_f32 v108, v108, v109
	v_cvt_pk_bf16_f32 v109, v110, v111
	v_cvt_pk_bf16_f32 v104, v104, v105
	v_cvt_pk_bf16_f32 v105, v106, v107
	v_cvt_pk_bf16_f32 v100, v100, v101
	v_cvt_pk_bf16_f32 v101, v102, v103
	global_store_dwordx2 v[114:115], v[112:113], off
	global_store_dwordx2 v[114:115], v[108:109], off offset:512
	global_store_dwordx2 v[114:115], v[104:105], off offset:1024
	global_store_dwordx2 v[114:115], v[100:101], off offset:1536

; __device__ __forceinline__ float wave_sum(float v) {
; #pragma unroll
;     for (int o = 1; o < 64; o <<= 1) v += __shfl_xor(v, o);
;     return v;
; }
.LBB0_717:
	v_pk_mul_f32 v[100:101], v[98:99], v[98:99]
	v_pk_mul_f32 v[102:103], v[96:97], v[96:97]
	s_ashr_i32 s25, s24, 31
	v_pk_mov_b32 v[104:105], v[102:103], v[100:101] op_sel:[1,0]
	v_mov_b32_e32 v103, v101
	v_pk_add_f32 v[100:101], v[104:105], v[102:103]
	v_pk_mul_f32 v[102:103], v[94:95], v[94:95]
	v_pk_add_f32 v[100:101], v[100:101], v[100:101] op_sel_hi:[0,1]
	v_pk_mul_f32 v[104:105], v[92:93], v[92:93]
	v_mul_f32_e32 v100, v88, v88
	v_pk_mov_b32 v[106:107], v[104:105], v[102:103] op_sel:[1,0]
	v_mov_b32_e32 v105, v103
	v_pk_add_f32 v[102:103], v[106:107], v[104:105]
	v_pk_fma_f32 v[104:105], v[88:89], v[88:89], v[100:101] op_sel_hi:[1,1,0]
	v_mul_f32_e32 v100, v90, v90
	v_pk_add_f32 v[102:103], v[102:103], v[102:103] op_sel_hi:[0,1]
	v_pk_fma_f32 v[106:107], v[90:91], v[90:91], v[100:101] op_sel_hi:[1,1,0]
	v_mul_f32_e32 v104, v84, v84
	v_mul_f32_e32 v106, v85, v85
	v_mul_f32_e32 v102, v86, v86
	v_mul_f32_e32 v100, v87, v87
	v_pk_add_f32 v[104:105], v[104:105], v[106:107]
	v_pk_add_f32 v[100:101], v[102:103], v[100:101]
	v_pk_add_f32 v[100:101], v[104:105], v[100:101]
	v_pk_mul_f32 v[98:99], v[22:23], v[98:99]
	v_add_f32_e32 v100, v100, v101
	v_pk_mul_f32 v[96:97], v[20:21], v[96:97]
	v_pk_mul_f32 v[94:95], v[30:31], v[94:95]
	s_nop 1
	v_add_f32_dpp v100, v100, v100 quad_perm:[1,0,3,2] row_mask:0xf bank_mask:0xf
	s_nop 1
	v_add_f32_dpp v100, v100, v100 quad_perm:[2,3,0,1] row_mask:0xf bank_mask:0xf
	s_nop 1
	v_add_f32_dpp v100, v100, v100 row_half_mirror row_mask:0xf bank_mask:0xf
	s_nop 1
	v_add_f32_dpp v100, v100, v100 row_mirror row_mask:0xf bank_mask:0xf
	s_nop 1
	v_add_f32_dpp v100, v100, v100 row_bcast:15 row_mask:0xa bank_mask:0xf
	s_nop 1
	v_add_f32_dpp v100, v100, v100 row_bcast:31 row_mask:0xc bank_mask:0xf
	s_nop 0
	v_readlane_b32 s32, v100, 63
	s_nop 1
	v_mov_b32_e32 v100, s32
	v_pk_mul_f32 v[92:93], v[28:29], v[92:93]
	v_pk_mul_f32 v[90:91], v[26:27], v[90:91]
	v_pk_mul_f32 v[88:89], v[24:25], v[88:89]
	v_pk_mul_f32 v[86:87], v[34:35], v[86:87]
	v_pk_mul_f32 v[84:85], v[32:33], v[84:85]
	s_lshl_b64 s[6:7], s[24:25], 11
	v_fmamk_f32 v100, v100, 0x3a800000, v228
	v_mul_f32_e32 v101, 0x4b800000, v100
	v_cmp_gt_f32_e32 vcc, s62, v100
	s_nop 1
	v_cndmask_b32_e32 v100, v100, v101, vcc
	v_rsq_f32_e32 v100, v100
	s_nop 0
	v_mul_f32_e32 v101, 0x45800000, v100
	v_cndmask_b32_e32 v100, v100, v101, vcc
	s_waitcnt vmcnt(0)
	v_pk_fma_f32 v[98:99], v[98:99], v[100:101], v[6:7] op_sel_hi:[1,0,1]
	v_pk_fma_f32 v[96:97], v[96:97], v[100:101], v[4:5] op_sel_hi:[1,0,1]
	v_pk_fma_f32 v[94:95], v[94:95], v[100:101], v[14:15] op_sel_hi:[1,0,1]
	v_pk_fma_f32 v[92:93], v[92:93], v[100:101], v[12:13] op_sel_hi:[1,0,1]
	v_pk_fma_f32 v[90:91], v[90:91], v[100:101], v[10:11] op_sel_hi:[1,0,1]
	v_pk_fma_f32 v[88:89], v[88:89], v[100:101], v[8:9] op_sel_hi:[1,0,1]
	v_pk_fma_f32 v[86:87], v[86:87], v[100:101], v[18:19] op_sel_hi:[1,0,1]
	v_pk_fma_f32 v[84:85], v[84:85], v[100:101], v[16:17] op_sel_hi:[1,0,1]
	v_cvt_pk_bf16_f32 v96, v96, v97
	v_cvt_pk_bf16_f32 v97, v98, v99
	v_lshl_add_u64 v[98:99], v[136:137], 0, s[6:7]
	v_cvt_pk_bf16_f32 v92, v92, v93
	v_cvt_pk_bf16_f32 v93, v94, v95
	v_cvt_pk_bf16_f32 v88, v88, v89
	v_cvt_pk_bf16_f32 v89, v90, v91
	v_cvt_pk_bf16_f32 v84, v84, v85
	v_cvt_pk_bf16_f32 v85, v86, v87
	global_store_dwordx2 v[98:99], v[96:97], off
	global_store_dwordx2 v[98:99], v[92:93], off offset:512
	global_store_dwordx2 v[98:99], v[88:89], off offset:1024
	global_store_dwordx2 v[98:99], v[84:85], off offset:1536

; __device__ __forceinline__ float bflo(unsigned w) { return __uint_as_float(w << 16); }
; __device__ __forceinline__ float bfhi(unsigned w) { return __uint_as_float(w & 0xffff0000u); }
; __device__ __forceinline__ void norm_phase(const Ctx& c, int s) {
;     ...
;                     for (int j = 0; j < 4; ++j) { v[j] = xf32 ? cu[k].v[j] : (f32x4){bflo(cu[k].xb[j].x), bfhi(cu[k].xb[j].x), bflo(cu[k].xb[j].y), bfhi(cu[k].xb[j].y)};
;                         fv[j] = (f32x4){bflo(cu[k].f[j].x), bfhi(cu[k].f[j].x), bflo(cu[k].f[j].y), bfhi(cu[k].f[j].y)}; }
;                     if (has_upd) { float p = cu[k].p; p += __shfl_xor(p, 1); p += __shfl_xor(p, 2); p += __shfl_xor(p, 4); p += __shfl_xor(p, 8); rf = rsqrtf(p * (1.0f / D) + EPS); }
;                     NORM_BODY(row, v, fv, rf);
.LBB0_722:
	s_nop 1
	v_add_f32_dpp v100, v123, v123 quad_perm:[1,0,3,2] row_mask:0xf bank_mask:0xf
	s_nop 1
	v_add_f32_dpp v100, v100, v100 quad_perm:[2,3,0,1] row_mask:0xf bank_mask:0xf
	s_nop 1
	v_add_f32_dpp v100, v100, v100 row_half_mirror row_mask:0xf bank_mask:0xf
	s_nop 1
	v_add_f32_dpp v100, v100, v100 row_mirror row_mask:0xf bank_mask:0xf
	s_ashr_i32 s25, s24, 31
	v_lshlrev_b32_e32 v104, 16, v195
	v_and_b32_e32 v105, 0xffff0000, v195
	s_lshl_b64 s[44:45], s[24:25], 12
	v_readlane_b32 s46, v254, 8
	v_readlane_b32 s47, v254, 9
	s_add_u32 s44, s46, s44
	v_lshlrev_b32_e32 v102, 16, v194
	v_and_b32_e32 v103, 0xffff0000, v194
	v_pk_mul_f32 v[102:103], v[36:37], v[102:103]
	v_pk_mul_f32 v[104:105], v[38:39], v[104:105]
	v_fmamk_f32 v100, v100, 0x3a800000, v228
	v_mul_f32_e32 v101, 0x4b800000, v100
	v_cmp_gt_f32_e32 vcc, s62, v100
	s_addc_u32 s45, s47, s45
	s_mov_b64 s[46:47], -1
	v_cndmask_b32_e32 v100, v100, v101, vcc
	v_rsq_f32_e32 v100, v100
	s_nop 0
	v_mul_f32_e32 v101, 0x45800000, v100
	v_cndmask_b32_e32 v100, v100, v101, vcc
	v_pk_fma_f32 v[98:99], v[104:105], v[100:101], v[98:99] op_sel_hi:[1,0,1]
	v_pk_fma_f32 v[96:97], v[102:103], v[100:101], v[96:97] op_sel_hi:[1,0,1]
	s_and_b64 vcc, exec, s[12:13]
	s_cbranch_vccz .LBB0_724
	v_cvt_pk_bf16_f32 v102, v96, v97
	v_cvt_pk_bf16_f32 v103, v98, v99
	global_store_dwordx2 v120, v[102:103], s[44:45]
	s_mov_b64 s[46:47], 0
